# s_setprio 1 raised already at the h2 row fetch (before the first gather batch) in G1
# baseline (speedup 1.0000x reference)
.LBB0_1012:
	s_or_b64 exec, exec, s[42:43]
	s_setprio 1
	v_ashrrev_i32_e32 v117, 31, v116
	v_lshlrev_b64 v[0:1], 11, v[116:117]
	s_waitcnt lgkmcnt(0)
	v_lshl_add_u64 v[0:1], v[120:121], 0, v[0:1]
	global_load_dwordx2 v[2:3], v[0:1], off
	global_load_dwordx2 v[4:5], v[0:1], off offset:256
	global_load_dwordx2 v[6:7], v[0:1], off offset:512
	global_load_dwordx2 v[8:9], v[0:1], off offset:768
	global_load_dwordx2 v[10:11], v[0:1], off offset:1024
	global_load_dwordx2 v[12:13], v[0:1], off offset:1280
	global_load_dwordx2 v[14:15], v[0:1], off offset:1536
	s_nop 0
	global_load_dwordx2 v[0:1], v[0:1], off offset:1792
	s_movk_i32 s63, 0xffe0
	v_mov_b32_e32 v183, v134
	s_waitcnt vmcnt(7)
	v_lshlrev_b32_e32 v16, 16, v2
	v_and_b32_e32 v2, 0xffff0000, v2
	v_lshlrev_b32_e32 v17, 16, v3
	v_and_b32_e32 v3, 0xffff0000, v3
	s_waitcnt vmcnt(6)
	v_lshlrev_b32_e32 v18, 16, v4
	v_and_b32_e32 v4, 0xffff0000, v4
	v_lshlrev_b32_e32 v19, 16, v5
	v_and_b32_e32 v5, 0xffff0000, v5
	s_waitcnt vmcnt(5)
	v_lshlrev_b32_e32 v20, 16, v6
	v_and_b32_e32 v6, 0xffff0000, v6
	v_lshlrev_b32_e32 v21, 16, v7
	v_and_b32_e32 v7, 0xffff0000, v7
	s_waitcnt vmcnt(4)
	v_lshlrev_b32_e32 v22, 16, v8
	v_and_b32_e32 v8, 0xffff0000, v8
	v_lshlrev_b32_e32 v23, 16, v9
	v_and_b32_e32 v9, 0xffff0000, v9
	s_waitcnt vmcnt(3)
	v_lshlrev_b32_e32 v24, 16, v10
	v_and_b32_e32 v10, 0xffff0000, v10
	v_lshlrev_b32_e32 v25, 16, v11
	v_and_b32_e32 v11, 0xffff0000, v11
	s_waitcnt vmcnt(2)
	v_lshlrev_b32_e32 v26, 16, v12
	v_and_b32_e32 v12, 0xffff0000, v12
	v_lshlrev_b32_e32 v27, 16, v13
	v_and_b32_e32 v13, 0xffff0000, v13
	s_waitcnt vmcnt(1)
	v_lshlrev_b32_e32 v28, 16, v14
	v_and_b32_e32 v14, 0xffff0000, v14
	v_lshlrev_b32_e32 v29, 16, v15
	v_and_b32_e32 v15, 0xffff0000, v15
	s_waitcnt vmcnt(0)
	v_lshlrev_b32_e32 v30, 16, v0
	v_and_b32_e32 v0, 0xffff0000, v0
	v_lshlrev_b32_e32 v31, 16, v1
	v_and_b32_e32 v1, 0xffff0000, v1
	v_cvt_pk_f16_f32 v166, v16, v2
	v_cvt_pk_f16_f32 v167, v17, v3
	v_cvt_pk_f16_f32 v168, v18, v4
	v_cvt_pk_f16_f32 v169, v19, v5
	v_cvt_pk_f16_f32 v170, v20, v6
	v_cvt_pk_f16_f32 v171, v21, v7
	v_cvt_pk_f16_f32 v172, v22, v8
	v_cvt_pk_f16_f32 v173, v23, v9
	v_cvt_pk_f16_f32 v174, v24, v10
	v_cvt_pk_f16_f32 v175, v25, v11
	v_cvt_pk_f16_f32 v177, v26, v12
	v_cvt_pk_f16_f32 v178, v27, v13
	v_cvt_pk_f16_f32 v179, v28, v14
	v_cvt_pk_f16_f32 v180, v29, v15
	v_cvt_pk_f16_f32 v181, v30, v0
	v_cvt_pk_f16_f32 v182, v31, v1
	s_branch .LBB0_1015
